# scan: only step 0 operands are read right after the chunk barrier; step 1 operands join the step-0 burst
# speedup vs baseline: 1.0004x; 1.0004x over previous
; DI void scan_task(const Params& p, int l, int isP, int b, int h, int rg, char* smem, const bool dry) {
;     ...
;     f32x4 w4 = *(const f32x4*)fw, a4 = *(const f32x4*)fa, b4 = *(const f32x4*)fb;
;     uint2 ur = *(const uint2*)pr, uk = *(const uint2*)pk;
;     float v = vb[0];
; #pragma unroll
;     for (int s = 0; s < 32; s++) {
;       f32x4 w4n = w4, a4n = a4, b4n = b4;
;       uint2 urn = ur, ukn = uk;
;       float vn = v;
;       if (s < 31) {
;         w4n = *(const f32x4*)(fw + (s + 1) * 64);
;         a4n = *(const f32x4*)(fa + (s + 1) * 64);
;         b4n = *(const f32x4*)(fb + (s + 1) * 64);
;         urn = *(const uint2*)(pr + (s + 1) * 128);
;         ukn = *(const uint2*)(pk + (s + 1) * 128);
;         vn = vb[(s + 1) * 16];
;       }
;       __builtin_amdgcn_sched_barrier(0);
;       const f32x2 klo = {__uint_as_float(uk.x << 16), __uint_as_float(uk.x & 0xFFFF0000u)};
;       const f32x2 khi = {__uint_as_float(uk.y << 16), __uint_as_float(uk.y & 0xFFFF0000u)};
;       const f32x2 rlo = {__uint_as_float(ur.x << 16), __uint_as_float(ur.x & 0xFFFF0000u)};
;       const f32x2 rhi = {__uint_as_float(ur.y << 16), __uint_as_float(ur.y & 0xFFFF0000u)};
;       const f32x2 vv = {v, v};
;       const f32x2 t = Sa * a4.lo + Sb * a4.hi;
;       const f32x2 na = Sa * w4.lo + vv * klo;
;       const f32x2 nb = Sb * w4.hi + vv * khi;
;       float sa = t.x + t.y;
;       float yp = yprev;
;       rowsum16x2(sa, yp);
;       if (s >= 1 && s <= 16) ykeep0 = (jq == s - 1) ? yp : ykeep0;
;       if (s >= 17) ykeep1 = (jq == s - 17) ? yp : ykeep1;
;       const f32x2 sv = {sa, sa};
;       Sa = na + sv * b4.lo;
;       Sb = nb + sv * b4.hi;
;       const f32x2 yy = Sa * rlo + Sb * rhi;
;       yprev = yy.x + yy.y;
;       w4 = w4n; a4 = a4n; b4 = b4n; ur = urn; uk = ukn; v = vn;
;     }
.Lstgs:
	ds_read_b128 v[12:15], v76 offset:4096
	ds_read_b128 v[24:27], v76 offset:16384
	ds_read_b128 v[48:51], v77 offset:20480
	ds_read_b128 v[8:11], v76 offset:0
	ds_read_b128 v[16:19], v76 offset:8192
	ds_read_b128 v[20:23], v76 offset:12288
	s_mov_b32 s16, 0
.Lscan_loop:
.Lscan_bodyA:
	s_waitcnt lgkmcnt(1)
	ds_read_b128 v[32:35], v76 offset:4352
	ds_read_b128 v[44:47], v76 offset:16640
	ds_read_b128 v[28:31], v76 offset:256
	ds_read_b128 v[36:39], v76 offset:8448
	ds_read_b128 v[40:43], v76 offset:12544
	ds_read_b128 v[228:231], v76 offset:4608
	ds_read_b128 v[240:243], v76 offset:16896
	ds_read_b128 v[224:227], v76 offset:512
	ds_read_b128 v[232:235], v76 offset:8704
	ds_read_b128 v[236:239], v76 offset:12800
	v_pk_mul_f32 v[56:57], v[4:5], v[12:13]
	v_pk_fma_f32 v[56:57], v[6:7], v[14:15], v[56:57]
	v_add_f32_e32 v58, v56, v57
	v_pk_mul_f32 v[60:61], v[48:49], v[24:25] op_sel_hi:[0,1]
	v_pk_mul_f32 v[62:63], v[48:49], v[26:27] op_sel_hi:[0,1]
	v_add_f32_dpp v58, v58, v58 quad_perm:[1,0,3,2] row_mask:0xf bank_mask:0xf bound_ctrl:1
	v_pk_fma_f32 v[60:61], v[4:5], v[8:9], v[60:61]
	v_pk_fma_f32 v[62:63], v[6:7], v[10:11], v[62:63]
	v_add_f32_dpp v58, v58, v58 quad_perm:[2,3,0,1] row_mask:0xf bank_mask:0xf bound_ctrl:1
	s_nop 1
	v_add_f32_dpp v58, v58, v58 row_half_mirror row_mask:0xf bank_mask:0xf bound_ctrl:1
	s_nop 1
	v_add_f32_dpp v58, v58, v58 row_mirror row_mask:0xf bank_mask:0xf bound_ctrl:1
	v_pk_fma_f32 v[4:5], v[58:59], v[16:17], v[60:61] op_sel_hi:[0,1,1]
	v_pk_fma_f32 v[6:7], v[58:59], v[18:19], v[62:63] op_sel_hi:[0,1,1]
	s_waitcnt lgkmcnt(6)
	ds_read_b128 v[12:15], v76 offset:4864
	ds_read_b128 v[24:27], v76 offset:17152
	ds_read_b128 v[8:11], v76 offset:768
	ds_read_b128 v[16:19], v76 offset:8960
	ds_read_b128 v[52:55], v77 offset:20496
	v_pk_mul_f32 v[56:57], v[4:5], v[32:33]
	v_pk_mul_f32 v[64:65], v[4:5], v[20:21]
	v_pk_fma_f32 v[56:57], v[6:7], v[34:35], v[56:57]
	v_pk_fma_f32 v[64:65], v[6:7], v[22:23], v[64:65]
	v_add_f32_e32 v58, v56, v57
	v_pk_mul_f32 v[60:61], v[48:49], v[44:45] op_sel:[1,0] op_sel_hi:[1,1]
	v_pk_mul_f32 v[62:63], v[48:49], v[46:47] op_sel:[1,0] op_sel_hi:[1,1]
	v_add_f32_dpp v58, v58, v58 quad_perm:[1,0,3,2] row_mask:0xf bank_mask:0xf bound_ctrl:1
	v_pk_fma_f32 v[60:61], v[4:5], v[28:29], v[60:61]
	v_add_f32_e32 v66, v64, v65
	v_add_f32_dpp v58, v58, v58 quad_perm:[2,3,0,1] row_mask:0xf bank_mask:0xf bound_ctrl:1
	v_pk_fma_f32 v[62:63], v[6:7], v[30:31], v[62:63]
	s_nop 0
	v_add_f32_dpp v58, v58, v58 row_half_mirror row_mask:0xf bank_mask:0xf bound_ctrl:1
	ds_read_b128 v[20:23], v76 offset:13056
	s_nop 0
	v_add_f32_dpp v58, v58, v58 row_mirror row_mask:0xf bank_mask:0xf bound_ctrl:1
	v_pk_fma_f32 v[4:5], v[58:59], v[36:37], v[60:61] op_sel_hi:[0,1,1]
	v_pk_fma_f32 v[6:7], v[58:59], v[38:39], v[62:63] op_sel_hi:[0,1,1]
	s_waitcnt lgkmcnt(7)
	ds_read_b128 v[32:35], v76 offset:5120
	ds_read_b128 v[44:47], v76 offset:17408
	ds_read_b128 v[28:31], v76 offset:1024
	ds_read_b128 v[36:39], v76 offset:9216
	v_pk_mul_f32 v[56:57], v[4:5], v[228:229]
	v_pk_mul_f32 v[64:65], v[4:5], v[40:41]
	v_pk_fma_f32 v[56:57], v[6:7], v[230:231], v[56:57]
	v_pk_fma_f32 v[64:65], v[6:7], v[42:43], v[64:65]
	v_add_f32_e32 v58, v56, v57
	v_pk_mul_f32 v[60:61], v[50:51], v[240:241] op_sel_hi:[0,1]
	v_pk_mul_f32 v[62:63], v[50:51], v[242:243] op_sel_hi:[0,1]
	v_add_f32_dpp v58, v58, v58 quad_perm:[1,0,3,2] row_mask:0xf bank_mask:0xf bound_ctrl:1
	v_pk_fma_f32 v[60:61], v[4:5], v[224:225], v[60:61]
	v_add_f32_e32 v67, v64, v65
	v_add_f32_dpp v58, v58, v58 quad_perm:[2,3,0,1] row_mask:0xf bank_mask:0xf bound_ctrl:1
	v_pk_fma_f32 v[62:63], v[6:7], v[226:227], v[62:63]
	v_add_f32_dpp v68, v66, v66 row_mirror row_mask:0xf bank_mask:0x3
	v_add_f32_dpp v58, v58, v58 row_half_mirror row_mask:0xf bank_mask:0xf bound_ctrl:1
	s_nop 0
	v_add_f32_dpp v68, v67, v67 row_mirror row_mask:0xf bank_mask:0xc
	ds_read_b128 v[40:43], v76 offset:13312
	v_add_f32_dpp v58, v58, v58 row_mirror row_mask:0xf bank_mask:0xf bound_ctrl:1
	v_pk_fma_f32 v[4:5], v[58:59], v[232:233], v[60:61] op_sel_hi:[0,1,1]
	v_pk_fma_f32 v[6:7], v[58:59], v[234:235], v[62:63] op_sel_hi:[0,1,1]
	s_waitcnt lgkmcnt(7)
	ds_read_b128 v[228:231], v76 offset:5376
	ds_read_b128 v[240:243], v76 offset:17664
	ds_read_b128 v[224:227], v76 offset:1280
	ds_read_b128 v[232:235], v76 offset:9472
	v_pk_mul_f32 v[56:57], v[4:5], v[12:13]
	v_pk_mul_f32 v[64:65], v[4:5], v[236:237]
	v_pk_fma_f32 v[56:57], v[6:7], v[14:15], v[56:57]
	v_pk_fma_f32 v[64:65], v[6:7], v[238:239], v[64:65]
	v_add_f32_e32 v58, v56, v57
	v_pk_mul_f32 v[60:61], v[50:51], v[24:25] op_sel:[1,0] op_sel_hi:[1,1]
	v_pk_mul_f32 v[62:63], v[50:51], v[26:27] op_sel:[1,0] op_sel_hi:[1,1]
	v_add_f32_dpp v58, v58, v58 quad_perm:[1,0,3,2] row_mask:0xf bank_mask:0xf bound_ctrl:1
	v_pk_fma_f32 v[60:61], v[4:5], v[8:9], v[60:61]
	v_add_f32_e32 v66, v64, v65
	v_add_f32_dpp v58, v58, v58 quad_perm:[2,3,0,1] row_mask:0xf bank_mask:0xf bound_ctrl:1
	v_pk_fma_f32 v[62:63], v[6:7], v[10:11], v[62:63]
	s_nop 0
	v_add_f32_dpp v58, v58, v58 row_half_mirror row_mask:0xf bank_mask:0xf bound_ctrl:1
	ds_read_b128 v[236:239], v76 offset:13568
	s_nop 0
	v_add_f32_dpp v58, v58, v58 row_mirror row_mask:0xf bank_mask:0xf bound_ctrl:1
	v_pk_fma_f32 v[4:5], v[58:59], v[16:17], v[60:61] op_sel_hi:[0,1,1]
	v_pk_fma_f32 v[6:7], v[58:59], v[18:19], v[62:63] op_sel_hi:[0,1,1]
	s_waitcnt lgkmcnt(6)
; DI void scan_task(const Params& p, int l, int isP, int b, int h, int rg, char* smem, const bool dry) {
;     ...
;     for (int s = 0; s < 32; s++) {
;       f32x4 w4n = w4, a4n = a4, b4n = b4;
;       uint2 urn = ur, ukn = uk;
;       float vn = v;
;       if (s < 31) {
;         w4n = *(const f32x4*)(fw + (s + 1) * 64);
;         a4n = *(const f32x4*)(fa + (s + 1) * 64);
;         b4n = *(const f32x4*)(fb + (s + 1) * 64);
;         urn = *(const uint2*)(pr + (s + 1) * 128);
;         ukn = *(const uint2*)(pk + (s + 1) * 128);
;         vn = vb[(s + 1) * 16];
;       }
;       __builtin_amdgcn_sched_barrier(0);
;       const f32x2 klo = {__uint_as_float(uk.x << 16), __uint_as_float(uk.x & 0xFFFF0000u)};
;       const f32x2 khi = {__uint_as_float(uk.y << 16), __uint_as_float(uk.y & 0xFFFF0000u)};
;       const f32x2 rlo = {__uint_as_float(ur.x << 16), __uint_as_float(ur.x & 0xFFFF0000u)};
;       const f32x2 rhi = {__uint_as_float(ur.y << 16), __uint_as_float(ur.y & 0xFFFF0000u)};
;       const f32x2 vv = {v, v};
;       const f32x2 t = Sa * a4.lo + Sb * a4.hi;
;       const f32x2 na = Sa * w4.lo + vv * klo;
;       const f32x2 nb = Sb * w4.hi + vv * khi;
;       float sa = t.x + t.y;
;       float yp = yprev;
;       rowsum16x2(sa, yp);
;       if (s >= 1 && s <= 16) ykeep0 = (jq == s - 1) ? yp : ykeep0;
;       if (s >= 17) ykeep1 = (jq == s - 17) ? yp : ykeep1;
;       const f32x2 sv = {sa, sa};
;       Sa = na + sv * b4.lo;
;       Sb = nb + sv * b4.hi;
;       const f32x2 yy = Sa * rlo + Sb * rhi;
;       yprev = yy.x + yy.y;
;       w4 = w4n; a4 = a4n; b4 = b4n; ur = urn; uk = ukn; v = vn;
;     }
	ds_read_b128 v[12:15], v76 offset:5632
	ds_read_b128 v[24:27], v76 offset:17920
	ds_read_b128 v[8:11], v76 offset:1536
	ds_read_b128 v[16:19], v76 offset:9728
	v_pk_mul_f32 v[56:57], v[4:5], v[32:33]
	v_pk_mul_f32 v[64:65], v[4:5], v[20:21]
	v_pk_fma_f32 v[56:57], v[6:7], v[34:35], v[56:57]
	v_pk_fma_f32 v[64:65], v[6:7], v[22:23], v[64:65]
	v_add_f32_e32 v58, v56, v57
	v_pk_mul_f32 v[60:61], v[52:53], v[44:45] op_sel_hi:[0,1]
	v_pk_mul_f32 v[62:63], v[52:53], v[46:47] op_sel_hi:[0,1]
	v_add_f32_dpp v58, v58, v58 quad_perm:[1,0,3,2] row_mask:0xf bank_mask:0xf bound_ctrl:1
	v_pk_fma_f32 v[60:61], v[4:5], v[28:29], v[60:61]
	v_add_f32_e32 v67, v64, v65
	v_add_f32_dpp v58, v58, v58 quad_perm:[2,3,0,1] row_mask:0xf bank_mask:0xf bound_ctrl:1
	v_pk_fma_f32 v[62:63], v[6:7], v[30:31], v[62:63]
	v_add_f32_dpp v69, v66, v66 row_mirror row_mask:0xf bank_mask:0x3
	v_add_f32_dpp v58, v58, v58 row_half_mirror row_mask:0xf bank_mask:0xf bound_ctrl:1
	s_nop 0
	v_add_f32_dpp v69, v67, v67 row_mirror row_mask:0xf bank_mask:0xc
	ds_read_b128 v[20:23], v76 offset:13824
	v_add_f32_dpp v58, v58, v58 row_mirror row_mask:0xf bank_mask:0xf bound_ctrl:1
	v_pk_fma_f32 v[4:5], v[58:59], v[36:37], v[60:61] op_sel_hi:[0,1,1]
	v_pk_fma_f32 v[6:7], v[58:59], v[38:39], v[62:63] op_sel_hi:[0,1,1]
	s_waitcnt lgkmcnt(6)
	ds_read_b128 v[32:35], v76 offset:5888
	ds_read_b128 v[44:47], v76 offset:18176
	ds_read_b128 v[28:31], v76 offset:1792
	ds_read_b128 v[36:39], v76 offset:9984
	ds_read_b128 v[48:51], v77 offset:20512
	v_pk_mul_f32 v[56:57], v[4:5], v[228:229]
	v_pk_mul_f32 v[64:65], v[4:5], v[40:41]
	v_pk_fma_f32 v[56:57], v[6:7], v[230:231], v[56:57]
	v_pk_fma_f32 v[64:65], v[6:7], v[42:43], v[64:65]
	v_add_f32_e32 v58, v56, v57
	v_pk_mul_f32 v[60:61], v[52:53], v[240:241] op_sel:[1,0] op_sel_hi:[1,1]
	v_pk_mul_f32 v[62:63], v[52:53], v[242:243] op_sel:[1,0] op_sel_hi:[1,1]
	v_add_f32_dpp v58, v58, v58 quad_perm:[1,0,3,2] row_mask:0xf bank_mask:0xf bound_ctrl:1
	v_pk_fma_f32 v[60:61], v[4:5], v[224:225], v[60:61]
	v_add_f32_e32 v66, v64, v65
	v_add_f32_dpp v58, v58, v58 quad_perm:[2,3,0,1] row_mask:0xf bank_mask:0xf bound_ctrl:1
	v_pk_fma_f32 v[62:63], v[6:7], v[226:227], v[62:63]
	v_add_f32_dpp v68, v68, v68 row_half_mirror row_mask:0xf bank_mask:0x5
	v_add_f32_dpp v58, v58, v58 row_half_mirror row_mask:0xf bank_mask:0xf bound_ctrl:1
	s_nop 0
	v_add_f32_dpp v68, v69, v69 row_half_mirror row_mask:0xf bank_mask:0xa
	ds_read_b128 v[40:43], v76 offset:14080
	v_add_f32_dpp v58, v58, v58 row_mirror row_mask:0xf bank_mask:0xf bound_ctrl:1
	v_pk_fma_f32 v[4:5], v[58:59], v[232:233], v[60:61] op_sel_hi:[0,1,1]
	v_pk_fma_f32 v[6:7], v[58:59], v[234:235], v[62:63] op_sel_hi:[0,1,1]
	s_waitcnt lgkmcnt(7)
	ds_read_b128 v[228:231], v76 offset:6144
	ds_read_b128 v[240:243], v76 offset:18432
	ds_read_b128 v[224:227], v76 offset:2048
	ds_read_b128 v[232:235], v76 offset:10240
	v_pk_mul_f32 v[56:57], v[4:5], v[12:13]
	v_pk_mul_f32 v[64:65], v[4:5], v[236:237]
	v_pk_fma_f32 v[56:57], v[6:7], v[14:15], v[56:57]
	v_pk_fma_f32 v[64:65], v[6:7], v[238:239], v[64:65]
	v_add_f32_e32 v58, v56, v57
	v_pk_mul_f32 v[60:61], v[54:55], v[24:25] op_sel_hi:[0,1]
	v_pk_mul_f32 v[62:63], v[54:55], v[26:27] op_sel_hi:[0,1]
	v_add_f32_dpp v58, v58, v58 quad_perm:[1,0,3,2] row_mask:0xf bank_mask:0xf bound_ctrl:1
	v_pk_fma_f32 v[60:61], v[4:5], v[8:9], v[60:61]
	v_add_f32_e32 v67, v64, v65
	v_add_f32_dpp v58, v58, v58 quad_perm:[2,3,0,1] row_mask:0xf bank_mask:0xf bound_ctrl:1
	v_pk_fma_f32 v[62:63], v[6:7], v[10:11], v[62:63]
	v_add_f32_dpp v70, v66, v66 row_mirror row_mask:0xf bank_mask:0x3
	v_add_f32_dpp v58, v58, v58 row_half_mirror row_mask:0xf bank_mask:0xf bound_ctrl:1
	s_nop 0
	v_add_f32_dpp v70, v67, v67 row_mirror row_mask:0xf bank_mask:0xc
	ds_read_b128 v[236:239], v76 offset:14336
	v_add_f32_dpp v58, v58, v58 row_mirror row_mask:0xf bank_mask:0xf bound_ctrl:1
	v_pk_fma_f32 v[4:5], v[58:59], v[16:17], v[60:61] op_sel_hi:[0,1,1]
	v_pk_fma_f32 v[6:7], v[58:59], v[18:19], v[62:63] op_sel_hi:[0,1,1]
	s_waitcnt lgkmcnt(7)
	ds_read_b128 v[12:15], v76 offset:6400
	ds_read_b128 v[24:27], v76 offset:18688
	ds_read_b128 v[8:11], v76 offset:2304
	ds_read_b128 v[16:19], v76 offset:10496
	v_pk_mul_f32 v[56:57], v[4:5], v[32:33]
	v_pk_mul_f32 v[64:65], v[4:5], v[20:21]
	v_pk_fma_f32 v[56:57], v[6:7], v[34:35], v[56:57]
	v_pk_fma_f32 v[64:65], v[6:7], v[22:23], v[64:65]
	v_add_f32_e32 v58, v56, v57
	v_pk_mul_f32 v[60:61], v[54:55], v[44:45] op_sel:[1,0] op_sel_hi:[1,1]
	v_pk_mul_f32 v[62:63], v[54:55], v[46:47] op_sel:[1,0] op_sel_hi:[1,1]
	v_add_f32_dpp v58, v58, v58 quad_perm:[1,0,3,2] row_mask:0xf bank_mask:0xf bound_ctrl:1
	v_pk_fma_f32 v[60:61], v[4:5], v[28:29], v[60:61]
	v_add_f32_e32 v66, v64, v65
	v_add_f32_dpp v58, v58, v58 quad_perm:[2,3,0,1] row_mask:0xf bank_mask:0xf bound_ctrl:1
	v_pk_fma_f32 v[62:63], v[6:7], v[30:31], v[62:63]
	s_nop 0
	v_add_f32_dpp v58, v58, v58 row_half_mirror row_mask:0xf bank_mask:0xf bound_ctrl:1
	ds_read_b128 v[20:23], v76 offset:14592
	s_nop 0
	v_add_f32_dpp v58, v58, v58 row_mirror row_mask:0xf bank_mask:0xf bound_ctrl:1
	v_pk_fma_f32 v[4:5], v[58:59], v[36:37], v[60:61] op_sel_hi:[0,1,1]
	v_pk_fma_f32 v[6:7], v[58:59], v[38:39], v[62:63] op_sel_hi:[0,1,1]
	s_waitcnt lgkmcnt(6)
; DI void scan_task(const Params& p, int l, int isP, int b, int h, int rg, char* smem, const bool dry) {
;     ...
;     for (int s = 0; s < 32; s++) {
;       f32x4 w4n = w4, a4n = a4, b4n = b4;
;       uint2 urn = ur, ukn = uk;
;       float vn = v;
;       if (s < 31) {
;         w4n = *(const f32x4*)(fw + (s + 1) * 64);
;         a4n = *(const f32x4*)(fa + (s + 1) * 64);
;         b4n = *(const f32x4*)(fb + (s + 1) * 64);
;         urn = *(const uint2*)(pr + (s + 1) * 128);
;         ukn = *(const uint2*)(pk + (s + 1) * 128);
;         vn = vb[(s + 1) * 16];
;       }
;       __builtin_amdgcn_sched_barrier(0);
;       const f32x2 klo = {__uint_as_float(uk.x << 16), __uint_as_float(uk.x & 0xFFFF0000u)};
;       const f32x2 khi = {__uint_as_float(uk.y << 16), __uint_as_float(uk.y & 0xFFFF0000u)};
;       const f32x2 rlo = {__uint_as_float(ur.x << 16), __uint_as_float(ur.x & 0xFFFF0000u)};
;       const f32x2 rhi = {__uint_as_float(ur.y << 16), __uint_as_float(ur.y & 0xFFFF0000u)};
;       const f32x2 vv = {v, v};
;       const f32x2 t = Sa * a4.lo + Sb * a4.hi;
;       const f32x2 na = Sa * w4.lo + vv * klo;
;       const f32x2 nb = Sb * w4.hi + vv * khi;
;       float sa = t.x + t.y;
;       float yp = yprev;
;       rowsum16x2(sa, yp);
;       if (s >= 1 && s <= 16) ykeep0 = (jq == s - 1) ? yp : ykeep0;
;       if (s >= 17) ykeep1 = (jq == s - 17) ? yp : ykeep1;
;       const f32x2 sv = {sa, sa};
;       Sa = na + sv * b4.lo;
;       Sb = nb + sv * b4.hi;
;       const f32x2 yy = Sa * rlo + Sb * rhi;
;       yprev = yy.x + yy.y;
;       w4 = w4n; a4 = a4n; b4 = b4n; ur = urn; uk = ukn; v = vn;
;     }
	ds_read_b128 v[32:35], v76 offset:6656
	ds_read_b128 v[44:47], v76 offset:18944
	ds_read_b128 v[28:31], v76 offset:2560
	ds_read_b128 v[36:39], v76 offset:10752
	v_pk_mul_f32 v[56:57], v[4:5], v[228:229]
	v_pk_mul_f32 v[64:65], v[4:5], v[40:41]
	v_pk_fma_f32 v[56:57], v[6:7], v[230:231], v[56:57]
	v_pk_fma_f32 v[64:65], v[6:7], v[42:43], v[64:65]
	v_add_f32_e32 v58, v56, v57
	v_pk_mul_f32 v[60:61], v[48:49], v[240:241] op_sel_hi:[0,1]
	v_pk_mul_f32 v[62:63], v[48:49], v[242:243] op_sel_hi:[0,1]
	v_add_f32_dpp v58, v58, v58 quad_perm:[1,0,3,2] row_mask:0xf bank_mask:0xf bound_ctrl:1
	v_pk_fma_f32 v[60:61], v[4:5], v[224:225], v[60:61]
	v_add_f32_e32 v67, v64, v65
	v_add_f32_dpp v58, v58, v58 quad_perm:[2,3,0,1] row_mask:0xf bank_mask:0xf bound_ctrl:1
	v_pk_fma_f32 v[62:63], v[6:7], v[226:227], v[62:63]
	v_add_f32_dpp v71, v66, v66 row_mirror row_mask:0xf bank_mask:0x3
	v_add_f32_dpp v58, v58, v58 row_half_mirror row_mask:0xf bank_mask:0xf bound_ctrl:1
	s_nop 0
	v_add_f32_dpp v71, v67, v67 row_mirror row_mask:0xf bank_mask:0xc
	ds_read_b128 v[40:43], v76 offset:14848
	v_add_f32_dpp v58, v58, v58 row_mirror row_mask:0xf bank_mask:0xf bound_ctrl:1
	v_pk_fma_f32 v[4:5], v[58:59], v[232:233], v[60:61] op_sel_hi:[0,1,1]
	v_pk_fma_f32 v[6:7], v[58:59], v[234:235], v[62:63] op_sel_hi:[0,1,1]
	s_waitcnt lgkmcnt(6)
	ds_read_b128 v[228:231], v76 offset:6912
	ds_read_b128 v[240:243], v76 offset:19200
	ds_read_b128 v[224:227], v76 offset:2816
	ds_read_b128 v[232:235], v76 offset:11008
	ds_read_b128 v[52:55], v77 offset:20528
	v_pk_mul_f32 v[56:57], v[4:5], v[12:13]
	v_pk_mul_f32 v[64:65], v[4:5], v[236:237]
	v_pk_fma_f32 v[56:57], v[6:7], v[14:15], v[56:57]
	v_pk_fma_f32 v[64:65], v[6:7], v[238:239], v[64:65]
	v_add_f32_e32 v58, v56, v57
	v_pk_mul_f32 v[60:61], v[48:49], v[24:25] op_sel:[1,0] op_sel_hi:[1,1]
	v_pk_mul_f32 v[62:63], v[48:49], v[26:27] op_sel:[1,0] op_sel_hi:[1,1]
	v_add_f32_dpp v58, v58, v58 quad_perm:[1,0,3,2] row_mask:0xf bank_mask:0xf bound_ctrl:1
	v_pk_fma_f32 v[60:61], v[4:5], v[8:9], v[60:61]
	v_add_f32_e32 v66, v64, v65
	v_add_f32_dpp v58, v58, v58 quad_perm:[2,3,0,1] row_mask:0xf bank_mask:0xf bound_ctrl:1
	v_pk_fma_f32 v[62:63], v[6:7], v[10:11], v[62:63]
	v_add_f32_dpp v70, v70, v70 row_half_mirror row_mask:0xf bank_mask:0x5
	v_add_f32_dpp v58, v58, v58 row_half_mirror row_mask:0xf bank_mask:0xf bound_ctrl:1
	s_nop 0
	v_add_f32_dpp v70, v71, v71 row_half_mirror row_mask:0xf bank_mask:0xa
	ds_read_b128 v[236:239], v76 offset:15104
	v_add_f32_dpp v58, v58, v58 row_mirror row_mask:0xf bank_mask:0xf bound_ctrl:1
	v_pk_fma_f32 v[4:5], v[58:59], v[16:17], v[60:61] op_sel_hi:[0,1,1]
	v_pk_fma_f32 v[6:7], v[58:59], v[18:19], v[62:63] op_sel_hi:[0,1,1]
	s_waitcnt lgkmcnt(7)
	ds_read_b128 v[12:15], v76 offset:7168
	ds_read_b128 v[24:27], v76 offset:19456
	ds_read_b128 v[8:11], v76 offset:3072
	ds_read_b128 v[16:19], v76 offset:11264
	v_pk_mul_f32 v[56:57], v[4:5], v[32:33]
	v_pk_mul_f32 v[64:65], v[4:5], v[20:21]
	v_pk_fma_f32 v[56:57], v[6:7], v[34:35], v[56:57]
	v_pk_fma_f32 v[64:65], v[6:7], v[22:23], v[64:65]
	v_add_f32_e32 v58, v56, v57
	v_pk_mul_f32 v[60:61], v[50:51], v[44:45] op_sel_hi:[0,1]
	v_pk_mul_f32 v[62:63], v[50:51], v[46:47] op_sel_hi:[0,1]
	v_add_f32_dpp v58, v58, v58 quad_perm:[1,0,3,2] row_mask:0xf bank_mask:0xf bound_ctrl:1
	v_pk_fma_f32 v[60:61], v[4:5], v[28:29], v[60:61]
	v_add_f32_e32 v67, v64, v65
	v_add_f32_dpp v58, v58, v58 quad_perm:[2,3,0,1] row_mask:0xf bank_mask:0xf bound_ctrl:1
	v_pk_fma_f32 v[62:63], v[6:7], v[30:31], v[62:63]
	v_add_f32_dpp v72, v66, v66 row_mirror row_mask:0xf bank_mask:0x3
	v_add_f32_dpp v58, v58, v58 row_half_mirror row_mask:0xf bank_mask:0xf bound_ctrl:1
	s_nop 0
	v_add_f32_dpp v72, v67, v67 row_mirror row_mask:0xf bank_mask:0xc
	ds_read_b128 v[20:23], v76 offset:15360
	v_add_f32_dpp v58, v58, v58 row_mirror row_mask:0xf bank_mask:0xf bound_ctrl:1
	v_pk_fma_f32 v[4:5], v[58:59], v[36:37], v[60:61] op_sel_hi:[0,1,1]
	v_pk_fma_f32 v[6:7], v[58:59], v[38:39], v[62:63] op_sel_hi:[0,1,1]
	s_waitcnt lgkmcnt(7)
	ds_read_b128 v[32:35], v76 offset:7424
	ds_read_b128 v[44:47], v76 offset:19712
	ds_read_b128 v[28:31], v76 offset:3328
	ds_read_b128 v[36:39], v76 offset:11520
	v_pk_mul_f32 v[56:57], v[4:5], v[228:229]
	v_pk_mul_f32 v[64:65], v[4:5], v[40:41]
	v_pk_fma_f32 v[56:57], v[6:7], v[230:231], v[56:57]
	v_pk_fma_f32 v[64:65], v[6:7], v[42:43], v[64:65]
	v_add_f32_e32 v58, v56, v57
	v_pk_mul_f32 v[60:61], v[50:51], v[240:241] op_sel:[1,0] op_sel_hi:[1,1]
	v_pk_mul_f32 v[62:63], v[50:51], v[242:243] op_sel:[1,0] op_sel_hi:[1,1]
	v_add_f32_dpp v58, v58, v58 quad_perm:[1,0,3,2] row_mask:0xf bank_mask:0xf bound_ctrl:1
	v_pk_fma_f32 v[60:61], v[4:5], v[224:225], v[60:61]
	v_add_f32_e32 v66, v64, v65
	v_add_f32_dpp v58, v58, v58 quad_perm:[2,3,0,1] row_mask:0xf bank_mask:0xf bound_ctrl:1
	v_pk_fma_f32 v[62:63], v[6:7], v[226:227], v[62:63]
	s_nop 0
	v_add_f32_dpp v58, v58, v58 row_half_mirror row_mask:0xf bank_mask:0xf bound_ctrl:1
	ds_read_b128 v[40:43], v76 offset:15616
	s_nop 0
	v_add_f32_dpp v58, v58, v58 row_mirror row_mask:0xf bank_mask:0xf bound_ctrl:1
	v_pk_fma_f32 v[4:5], v[58:59], v[232:233], v[60:61] op_sel_hi:[0,1,1]
	v_pk_fma_f32 v[6:7], v[58:59], v[234:235], v[62:63] op_sel_hi:[0,1,1]
	s_waitcnt lgkmcnt(6)
; DI void scan_task(const Params& p, int l, int isP, int b, int h, int rg, char* smem, const bool dry) {
;     ...
;     for (int s = 0; s < 32; s++) {
;       f32x4 w4n = w4, a4n = a4, b4n = b4;
;       uint2 urn = ur, ukn = uk;
;       float vn = v;
;       if (s < 31) {
;         w4n = *(const f32x4*)(fw + (s + 1) * 64);
;         a4n = *(const f32x4*)(fa + (s + 1) * 64);
;         b4n = *(const f32x4*)(fb + (s + 1) * 64);
;         urn = *(const uint2*)(pr + (s + 1) * 128);
;         ukn = *(const uint2*)(pk + (s + 1) * 128);
;         vn = vb[(s + 1) * 16];
;       }
;       __builtin_amdgcn_sched_barrier(0);
;       const f32x2 klo = {__uint_as_float(uk.x << 16), __uint_as_float(uk.x & 0xFFFF0000u)};
;       const f32x2 khi = {__uint_as_float(uk.y << 16), __uint_as_float(uk.y & 0xFFFF0000u)};
;       const f32x2 rlo = {__uint_as_float(ur.x << 16), __uint_as_float(ur.x & 0xFFFF0000u)};
;       const f32x2 rhi = {__uint_as_float(ur.y << 16), __uint_as_float(ur.y & 0xFFFF0000u)};
;       const f32x2 vv = {v, v};
;       const f32x2 t = Sa * a4.lo + Sb * a4.hi;
;       const f32x2 na = Sa * w4.lo + vv * klo;
;       const f32x2 nb = Sb * w4.hi + vv * khi;
;       float sa = t.x + t.y;
;       float yp = yprev;
;       rowsum16x2(sa, yp);
;       if (s >= 1 && s <= 16) ykeep0 = (jq == s - 1) ? yp : ykeep0;
;       if (s >= 17) ykeep1 = (jq == s - 17) ? yp : ykeep1;
;       const f32x2 sv = {sa, sa};
;       Sa = na + sv * b4.lo;
;       Sb = nb + sv * b4.hi;
;       const f32x2 yy = Sa * rlo + Sb * rhi;
;       yprev = yy.x + yy.y;
;       w4 = w4n; a4 = a4n; b4 = b4n; ur = urn; uk = ukn; v = vn;
;     }
;     {
;       const float yl = rowsum16(yprev);
;       ykeep1 = (jq == 15) ? yl : ykeep1;
;     }
;     if (!dry) { yo[0] = ykeep0; yo[(size_t)16 * 512] = ykeep1; }
;     if (more) sstore((c + 1) & 1);
	ds_read_b128 v[228:231], v76 offset:7680
	ds_read_b128 v[240:243], v76 offset:19968
	ds_read_b128 v[224:227], v76 offset:3584
	ds_read_b128 v[232:235], v76 offset:11776
	v_pk_mul_f32 v[56:57], v[4:5], v[12:13]
	v_pk_mul_f32 v[64:65], v[4:5], v[236:237]
	v_pk_fma_f32 v[56:57], v[6:7], v[14:15], v[56:57]
	v_pk_fma_f32 v[64:65], v[6:7], v[238:239], v[64:65]
	v_add_f32_e32 v58, v56, v57
	v_pk_mul_f32 v[60:61], v[52:53], v[24:25] op_sel_hi:[0,1]
	v_pk_mul_f32 v[62:63], v[52:53], v[26:27] op_sel_hi:[0,1]
	v_add_f32_dpp v58, v58, v58 quad_perm:[1,0,3,2] row_mask:0xf bank_mask:0xf bound_ctrl:1
	v_pk_fma_f32 v[60:61], v[4:5], v[8:9], v[60:61]
	v_add_f32_e32 v67, v64, v65
	v_add_f32_dpp v58, v58, v58 quad_perm:[2,3,0,1] row_mask:0xf bank_mask:0xf bound_ctrl:1
	v_pk_fma_f32 v[62:63], v[6:7], v[10:11], v[62:63]
	v_add_f32_dpp v73, v66, v66 row_mirror row_mask:0xf bank_mask:0x3
	v_add_f32_dpp v58, v58, v58 row_half_mirror row_mask:0xf bank_mask:0xf bound_ctrl:1
	s_nop 0
	v_add_f32_dpp v73, v67, v67 row_mirror row_mask:0xf bank_mask:0xc
	ds_read_b128 v[236:239], v76 offset:15872
	v_add_f32_dpp v58, v58, v58 row_mirror row_mask:0xf bank_mask:0xf bound_ctrl:1
	v_pk_fma_f32 v[4:5], v[58:59], v[16:17], v[60:61] op_sel_hi:[0,1,1]
	v_pk_fma_f32 v[6:7], v[58:59], v[18:19], v[62:63] op_sel_hi:[0,1,1]
	s_waitcnt lgkmcnt(6)
	ds_read_b128 v[12:15], v76 offset:7936
	ds_read_b128 v[24:27], v76 offset:20224
	ds_read_b128 v[8:11], v76 offset:3840
	ds_read_b128 v[16:19], v76 offset:12032
	v_pk_mul_f32 v[56:57], v[4:5], v[32:33]
	v_pk_mul_f32 v[64:65], v[4:5], v[20:21]
	v_pk_fma_f32 v[56:57], v[6:7], v[34:35], v[56:57]
	v_pk_fma_f32 v[64:65], v[6:7], v[22:23], v[64:65]
	v_add_f32_e32 v58, v56, v57
	v_pk_mul_f32 v[60:61], v[52:53], v[44:45] op_sel:[1,0] op_sel_hi:[1,1]
	v_pk_mul_f32 v[62:63], v[52:53], v[46:47] op_sel:[1,0] op_sel_hi:[1,1]
	v_add_f32_dpp v58, v58, v58 quad_perm:[1,0,3,2] row_mask:0xf bank_mask:0xf bound_ctrl:1
	v_pk_fma_f32 v[60:61], v[4:5], v[28:29], v[60:61]
	v_add_f32_e32 v66, v64, v65
	v_add_f32_dpp v58, v58, v58 quad_perm:[2,3,0,1] row_mask:0xf bank_mask:0xf bound_ctrl:1
	v_pk_fma_f32 v[62:63], v[6:7], v[30:31], v[62:63]
	v_add_f32_dpp v72, v72, v72 row_half_mirror row_mask:0xf bank_mask:0x5
	v_add_f32_dpp v58, v58, v58 row_half_mirror row_mask:0xf bank_mask:0xf bound_ctrl:1
	s_nop 0
	v_add_f32_dpp v72, v73, v73 row_half_mirror row_mask:0xf bank_mask:0xa
	ds_read_b128 v[20:23], v76 offset:16128
	v_add_f32_dpp v58, v58, v58 row_mirror row_mask:0xf bank_mask:0xf bound_ctrl:1
	v_pk_fma_f32 v[4:5], v[58:59], v[36:37], v[60:61] op_sel_hi:[0,1,1]
	v_pk_fma_f32 v[6:7], v[58:59], v[38:39], v[62:63] op_sel_hi:[0,1,1]
	s_waitcnt lgkmcnt(6)
	v_pk_mul_f32 v[56:57], v[4:5], v[228:229]
	v_pk_mul_f32 v[64:65], v[4:5], v[40:41]
	v_pk_fma_f32 v[56:57], v[6:7], v[230:231], v[56:57]
	v_pk_fma_f32 v[64:65], v[6:7], v[42:43], v[64:65]
	v_add_f32_e32 v58, v56, v57
	v_pk_mul_f32 v[60:61], v[54:55], v[240:241] op_sel_hi:[0,1]
	v_pk_mul_f32 v[62:63], v[54:55], v[242:243] op_sel_hi:[0,1]
	v_add_f32_dpp v58, v58, v58 quad_perm:[1,0,3,2] row_mask:0xf bank_mask:0xf bound_ctrl:1
	v_pk_fma_f32 v[60:61], v[4:5], v[224:225], v[60:61]
	v_add_f32_e32 v67, v64, v65
	v_add_f32_dpp v58, v58, v58 quad_perm:[2,3,0,1] row_mask:0xf bank_mask:0xf bound_ctrl:1
	v_pk_fma_f32 v[62:63], v[6:7], v[226:227], v[62:63]
	v_add_f32_dpp v74, v66, v66 row_mirror row_mask:0xf bank_mask:0x3
	v_add_f32_dpp v58, v58, v58 row_half_mirror row_mask:0xf bank_mask:0xf bound_ctrl:1
	s_nop 0
	v_add_f32_dpp v74, v67, v67 row_mirror row_mask:0xf bank_mask:0xc
	v_add_f32_dpp v58, v58, v58 row_mirror row_mask:0xf bank_mask:0xf bound_ctrl:1
	v_pk_fma_f32 v[4:5], v[58:59], v[232:233], v[60:61] op_sel_hi:[0,1,1]
	v_pk_fma_f32 v[6:7], v[58:59], v[234:235], v[62:63] op_sel_hi:[0,1,1]
	s_waitcnt lgkmcnt(1)
	v_pk_mul_f32 v[56:57], v[4:5], v[12:13]
	v_pk_mul_f32 v[64:65], v[4:5], v[236:237]
	v_pk_fma_f32 v[56:57], v[6:7], v[14:15], v[56:57]
	v_pk_fma_f32 v[64:65], v[6:7], v[238:239], v[64:65]
	v_add_f32_e32 v58, v56, v57
	v_pk_mul_f32 v[60:61], v[54:55], v[24:25] op_sel:[1,0] op_sel_hi:[1,1]
	v_pk_mul_f32 v[62:63], v[54:55], v[26:27] op_sel:[1,0] op_sel_hi:[1,1]
	v_add_f32_dpp v58, v58, v58 quad_perm:[1,0,3,2] row_mask:0xf bank_mask:0xf bound_ctrl:1
	v_pk_fma_f32 v[60:61], v[4:5], v[8:9], v[60:61]
	v_add_f32_e32 v66, v64, v65
	v_add_f32_dpp v58, v58, v58 quad_perm:[2,3,0,1] row_mask:0xf bank_mask:0xf bound_ctrl:1
	v_pk_fma_f32 v[62:63], v[6:7], v[10:11], v[62:63]
	s_nop 0
	v_add_f32_dpp v58, v58, v58 row_half_mirror row_mask:0xf bank_mask:0xf bound_ctrl:1
	s_nop 1
	v_add_f32_dpp v58, v58, v58 row_mirror row_mask:0xf bank_mask:0xf bound_ctrl:1
	v_pk_fma_f32 v[4:5], v[58:59], v[16:17], v[60:61] op_sel_hi:[0,1,1]
	v_pk_fma_f32 v[6:7], v[58:59], v[18:19], v[62:63] op_sel_hi:[0,1,1]
	s_waitcnt lgkmcnt(0)
	v_pk_mul_f32 v[64:65], v[4:5], v[20:21]
	v_pk_fma_f32 v[64:65], v[6:7], v[22:23], v[64:65]
	v_add_f32_e32 v67, v64, v65
	s_cmp_lg_u32 s22, 0
	s_cbranch_scc1 .Lscan_w6A
	s_waitcnt vmcnt(0)
	s_branch .Lscan_wdA

; DI void scan_task(const Params& p, int l, int isP, int b, int h, int rg, char* smem, const bool dry) {
;     ...
;     f32x4 w4 = *(const f32x4*)fw, a4 = *(const f32x4*)fa, b4 = *(const f32x4*)fb;
;     uint2 ur = *(const uint2*)pr, uk = *(const uint2*)pk;
;     float v = vb[0];
; #pragma unroll
;     for (int s = 0; s < 32; s++) {
;       f32x4 w4n = w4, a4n = a4, b4n = b4;
;       uint2 urn = ur, ukn = uk;
;       float vn = v;
;       if (s < 31) {
;         w4n = *(const f32x4*)(fw + (s + 1) * 64);
;         a4n = *(const f32x4*)(fa + (s + 1) * 64);
;         b4n = *(const f32x4*)(fb + (s + 1) * 64);
;         urn = *(const uint2*)(pr + (s + 1) * 128);
;         ukn = *(const uint2*)(pk + (s + 1) * 128);
;         vn = vb[(s + 1) * 16];
;       }
;       __builtin_amdgcn_sched_barrier(0);
;       const f32x2 klo = {__uint_as_float(uk.x << 16), __uint_as_float(uk.x & 0xFFFF0000u)};
;       const f32x2 khi = {__uint_as_float(uk.y << 16), __uint_as_float(uk.y & 0xFFFF0000u)};
;       const f32x2 rlo = {__uint_as_float(ur.x << 16), __uint_as_float(ur.x & 0xFFFF0000u)};
;       const f32x2 rhi = {__uint_as_float(ur.y << 16), __uint_as_float(ur.y & 0xFFFF0000u)};
;       const f32x2 vv = {v, v};
;       const f32x2 t = Sa * a4.lo + Sb * a4.hi;
;       const f32x2 na = Sa * w4.lo + vv * klo;
;       const f32x2 nb = Sb * w4.hi + vv * khi;
;       float sa = t.x + t.y;
;       float yp = yprev;
;       rowsum16x2(sa, yp);
;       if (s >= 1 && s <= 16) ykeep0 = (jq == s - 1) ? yp : ykeep0;
;       if (s >= 17) ykeep1 = (jq == s - 17) ? yp : ykeep1;
;       const f32x2 sv = {sa, sa};
;       Sa = na + sv * b4.lo;
;       Sb = nb + sv * b4.hi;
;       const f32x2 yy = Sa * rlo + Sb * rhi;
;       yprev = yy.x + yy.y;
;       w4 = w4n; a4 = a4n; b4 = b4n; ur = urn; uk = ukn; v = vn;
;     }
;     {
;       const float yl = rowsum16(yprev);
;       ykeep1 = (jq == 15) ? yl : ykeep1;
;     }
;     if (!dry) { yo[0] = ykeep0; yo[(size_t)16 * 512] = ykeep1; }
.LstgbA:
	ds_read_b128 v[12:15], v76 offset:25600
	ds_read_b128 v[24:27], v76 offset:37888
	ds_read_b128 v[48:51], v77 offset:41984
	ds_read_b128 v[8:11], v76 offset:21504
	ds_read_b128 v[16:19], v76 offset:29696
	ds_read_b128 v[20:23], v76 offset:33792
	v_add_f32_dpp v75, v66, v66 row_mirror row_mask:0xf bank_mask:0x3
	v_add_f32_dpp v74, v74, v74 row_half_mirror row_mask:0xf bank_mask:0x5
	v_add_f32_dpp v68, v68, v68 quad_perm:[1,0,3,2] row_mask:0xf bank_mask:0xf
	v_add_f32_dpp v75, v67, v67 row_mirror row_mask:0xf bank_mask:0xc
	v_add_f32_dpp v70, v70, v70 quad_perm:[1,0,3,2] row_mask:0xf bank_mask:0xf
	v_add_f32_dpp v72, v72, v72 quad_perm:[1,0,3,2] row_mask:0xf bank_mask:0xf
	v_add_f32_dpp v74, v75, v75 row_half_mirror row_mask:0xf bank_mask:0xa
	v_add_f32_dpp v68, v68, v68 quad_perm:[2,3,0,1] row_mask:0xf bank_mask:0xf
	v_add_f32_dpp v70, v70, v70 quad_perm:[2,3,0,1] row_mask:0xf bank_mask:0xf
	v_add_f32_dpp v74, v74, v74 quad_perm:[1,0,3,2] row_mask:0xf bank_mask:0xf
	v_add_f32_dpp v72, v72, v72 quad_perm:[2,3,0,1] row_mask:0xf bank_mask:0xf
	v_cndmask_b32_e64 v68, v68, v70, s[18:19]
	v_add_f32_dpp v74, v74, v74 quad_perm:[2,3,0,1] row_mask:0xf bank_mask:0xf
	v_cndmask_b32_e64 v72, v72, v74, s[18:19]
	v_cndmask_b32_e64 v68, v68, v72, s[20:21]
	global_store_dword v83, v68, s[14:15]
	s_add_u32 s14, s14, 0x8000
	s_addc_u32 s15, s15, 0
.Lscan_bodyB:
	s_waitcnt lgkmcnt(1)
	ds_read_b128 v[32:35], v76 offset:25856
	ds_read_b128 v[44:47], v76 offset:38144
	ds_read_b128 v[28:31], v76 offset:21760
	ds_read_b128 v[36:39], v76 offset:29952
	ds_read_b128 v[40:43], v76 offset:34048
	ds_read_b128 v[228:231], v76 offset:26112
	ds_read_b128 v[240:243], v76 offset:38400
	ds_read_b128 v[224:227], v76 offset:22016
	ds_read_b128 v[232:235], v76 offset:30208
	ds_read_b128 v[236:239], v76 offset:34304
	v_pk_mul_f32 v[56:57], v[4:5], v[12:13]
	v_pk_fma_f32 v[56:57], v[6:7], v[14:15], v[56:57]
	v_add_f32_e32 v58, v56, v57
	v_pk_mul_f32 v[60:61], v[48:49], v[24:25] op_sel_hi:[0,1]
	v_pk_mul_f32 v[62:63], v[48:49], v[26:27] op_sel_hi:[0,1]
	v_add_f32_dpp v58, v58, v58 quad_perm:[1,0,3,2] row_mask:0xf bank_mask:0xf bound_ctrl:1
	v_pk_fma_f32 v[60:61], v[4:5], v[8:9], v[60:61]
	v_pk_fma_f32 v[62:63], v[6:7], v[10:11], v[62:63]
	v_add_f32_dpp v58, v58, v58 quad_perm:[2,3,0,1] row_mask:0xf bank_mask:0xf bound_ctrl:1
	s_nop 1
	v_add_f32_dpp v58, v58, v58 row_half_mirror row_mask:0xf bank_mask:0xf bound_ctrl:1
	s_nop 1
	v_add_f32_dpp v58, v58, v58 row_mirror row_mask:0xf bank_mask:0xf bound_ctrl:1
	v_pk_fma_f32 v[4:5], v[58:59], v[16:17], v[60:61] op_sel_hi:[0,1,1]
	v_pk_fma_f32 v[6:7], v[58:59], v[18:19], v[62:63] op_sel_hi:[0,1,1]
	s_waitcnt lgkmcnt(6)
	ds_read_b128 v[12:15], v76 offset:26368
	ds_read_b128 v[24:27], v76 offset:38656
	ds_read_b128 v[8:11], v76 offset:22272
	ds_read_b128 v[16:19], v76 offset:30464
	ds_read_b128 v[52:55], v77 offset:42000
	v_pk_mul_f32 v[56:57], v[4:5], v[32:33]
	v_pk_mul_f32 v[64:65], v[4:5], v[20:21]
	v_pk_fma_f32 v[56:57], v[6:7], v[34:35], v[56:57]
	v_pk_fma_f32 v[64:65], v[6:7], v[22:23], v[64:65]
	v_add_f32_e32 v58, v56, v57
	v_pk_mul_f32 v[60:61], v[48:49], v[44:45] op_sel:[1,0] op_sel_hi:[1,1]
	v_pk_mul_f32 v[62:63], v[48:49], v[46:47] op_sel:[1,0] op_sel_hi:[1,1]
	v_add_f32_dpp v58, v58, v58 quad_perm:[1,0,3,2] row_mask:0xf bank_mask:0xf bound_ctrl:1
	v_pk_fma_f32 v[60:61], v[4:5], v[28:29], v[60:61]
	v_add_f32_e32 v66, v64, v65
	v_add_f32_dpp v58, v58, v58 quad_perm:[2,3,0,1] row_mask:0xf bank_mask:0xf bound_ctrl:1
	v_pk_fma_f32 v[62:63], v[6:7], v[30:31], v[62:63]
	s_nop 0
	v_add_f32_dpp v58, v58, v58 row_half_mirror row_mask:0xf bank_mask:0xf bound_ctrl:1
	ds_read_b128 v[20:23], v76 offset:34560
	s_nop 0
	v_add_f32_dpp v58, v58, v58 row_mirror row_mask:0xf bank_mask:0xf bound_ctrl:1
	v_pk_fma_f32 v[4:5], v[58:59], v[36:37], v[60:61] op_sel_hi:[0,1,1]
	v_pk_fma_f32 v[6:7], v[58:59], v[38:39], v[62:63] op_sel_hi:[0,1,1]
	s_waitcnt lgkmcnt(7)
	ds_read_b128 v[32:35], v76 offset:26624
	ds_read_b128 v[44:47], v76 offset:38912
	ds_read_b128 v[28:31], v76 offset:22528
	ds_read_b128 v[36:39], v76 offset:30720
	v_pk_mul_f32 v[56:57], v[4:5], v[228:229]
	v_pk_mul_f32 v[64:65], v[4:5], v[40:41]
	v_pk_fma_f32 v[56:57], v[6:7], v[230:231], v[56:57]
	v_pk_fma_f32 v[64:65], v[6:7], v[42:43], v[64:65]
	v_add_f32_e32 v58, v56, v57
	v_pk_mul_f32 v[60:61], v[50:51], v[240:241] op_sel_hi:[0,1]
	v_pk_mul_f32 v[62:63], v[50:51], v[242:243] op_sel_hi:[0,1]
	v_add_f32_dpp v58, v58, v58 quad_perm:[1,0,3,2] row_mask:0xf bank_mask:0xf bound_ctrl:1
	v_pk_fma_f32 v[60:61], v[4:5], v[224:225], v[60:61]
	v_add_f32_e32 v67, v64, v65
	v_add_f32_dpp v58, v58, v58 quad_perm:[2,3,0,1] row_mask:0xf bank_mask:0xf bound_ctrl:1
	v_pk_fma_f32 v[62:63], v[6:7], v[226:227], v[62:63]
	v_add_f32_dpp v68, v66, v66 row_mirror row_mask:0xf bank_mask:0x3
	v_add_f32_dpp v58, v58, v58 row_half_mirror row_mask:0xf bank_mask:0xf bound_ctrl:1
	s_nop 0
	v_add_f32_dpp v68, v67, v67 row_mirror row_mask:0xf bank_mask:0xc
	ds_read_b128 v[40:43], v76 offset:34816
	v_add_f32_dpp v58, v58, v58 row_mirror row_mask:0xf bank_mask:0xf bound_ctrl:1
	v_pk_fma_f32 v[4:5], v[58:59], v[232:233], v[60:61] op_sel_hi:[0,1,1]
	v_pk_fma_f32 v[6:7], v[58:59], v[234:235], v[62:63] op_sel_hi:[0,1,1]
	s_waitcnt lgkmcnt(7)
; DI void scan_task(const Params& p, int l, int isP, int b, int h, int rg, char* smem, const bool dry) {
;     ...
;     for (int s = 0; s < 32; s++) {
;       f32x4 w4n = w4, a4n = a4, b4n = b4;
;       uint2 urn = ur, ukn = uk;
;       float vn = v;
;       if (s < 31) {
;         w4n = *(const f32x4*)(fw + (s + 1) * 64);
;         a4n = *(const f32x4*)(fa + (s + 1) * 64);
;         b4n = *(const f32x4*)(fb + (s + 1) * 64);
;         urn = *(const uint2*)(pr + (s + 1) * 128);
;         ukn = *(const uint2*)(pk + (s + 1) * 128);
;         vn = vb[(s + 1) * 16];
;       }
;       __builtin_amdgcn_sched_barrier(0);
;       const f32x2 klo = {__uint_as_float(uk.x << 16), __uint_as_float(uk.x & 0xFFFF0000u)};
;       const f32x2 khi = {__uint_as_float(uk.y << 16), __uint_as_float(uk.y & 0xFFFF0000u)};
;       const f32x2 rlo = {__uint_as_float(ur.x << 16), __uint_as_float(ur.x & 0xFFFF0000u)};
;       const f32x2 rhi = {__uint_as_float(ur.y << 16), __uint_as_float(ur.y & 0xFFFF0000u)};
;       const f32x2 vv = {v, v};
;       const f32x2 t = Sa * a4.lo + Sb * a4.hi;
;       const f32x2 na = Sa * w4.lo + vv * klo;
;       const f32x2 nb = Sb * w4.hi + vv * khi;
;       float sa = t.x + t.y;
;       float yp = yprev;
;       rowsum16x2(sa, yp);
;       if (s >= 1 && s <= 16) ykeep0 = (jq == s - 1) ? yp : ykeep0;
;       if (s >= 17) ykeep1 = (jq == s - 17) ? yp : ykeep1;
;       const f32x2 sv = {sa, sa};
;       Sa = na + sv * b4.lo;
;       Sb = nb + sv * b4.hi;
;       const f32x2 yy = Sa * rlo + Sb * rhi;
;       yprev = yy.x + yy.y;
;       w4 = w4n; a4 = a4n; b4 = b4n; ur = urn; uk = ukn; v = vn;
;     }
	ds_read_b128 v[228:231], v76 offset:26880
	ds_read_b128 v[240:243], v76 offset:39168
	ds_read_b128 v[224:227], v76 offset:22784
	ds_read_b128 v[232:235], v76 offset:30976
	v_pk_mul_f32 v[56:57], v[4:5], v[12:13]
	v_pk_mul_f32 v[64:65], v[4:5], v[236:237]
	v_pk_fma_f32 v[56:57], v[6:7], v[14:15], v[56:57]
	v_pk_fma_f32 v[64:65], v[6:7], v[238:239], v[64:65]
	v_add_f32_e32 v58, v56, v57
	v_pk_mul_f32 v[60:61], v[50:51], v[24:25] op_sel:[1,0] op_sel_hi:[1,1]
	v_pk_mul_f32 v[62:63], v[50:51], v[26:27] op_sel:[1,0] op_sel_hi:[1,1]
	v_add_f32_dpp v58, v58, v58 quad_perm:[1,0,3,2] row_mask:0xf bank_mask:0xf bound_ctrl:1
	v_pk_fma_f32 v[60:61], v[4:5], v[8:9], v[60:61]
	v_add_f32_e32 v66, v64, v65
	v_add_f32_dpp v58, v58, v58 quad_perm:[2,3,0,1] row_mask:0xf bank_mask:0xf bound_ctrl:1
	v_pk_fma_f32 v[62:63], v[6:7], v[10:11], v[62:63]
	s_nop 0
	v_add_f32_dpp v58, v58, v58 row_half_mirror row_mask:0xf bank_mask:0xf bound_ctrl:1
	ds_read_b128 v[236:239], v76 offset:35072
	s_nop 0
	v_add_f32_dpp v58, v58, v58 row_mirror row_mask:0xf bank_mask:0xf bound_ctrl:1
	v_pk_fma_f32 v[4:5], v[58:59], v[16:17], v[60:61] op_sel_hi:[0,1,1]
	v_pk_fma_f32 v[6:7], v[58:59], v[18:19], v[62:63] op_sel_hi:[0,1,1]
	s_waitcnt lgkmcnt(6)
	ds_read_b128 v[12:15], v76 offset:27136
	ds_read_b128 v[24:27], v76 offset:39424
	ds_read_b128 v[8:11], v76 offset:23040
	ds_read_b128 v[16:19], v76 offset:31232
	v_pk_mul_f32 v[56:57], v[4:5], v[32:33]
	v_pk_mul_f32 v[64:65], v[4:5], v[20:21]
	v_pk_fma_f32 v[56:57], v[6:7], v[34:35], v[56:57]
	v_pk_fma_f32 v[64:65], v[6:7], v[22:23], v[64:65]
	v_add_f32_e32 v58, v56, v57
	v_pk_mul_f32 v[60:61], v[52:53], v[44:45] op_sel_hi:[0,1]
	v_pk_mul_f32 v[62:63], v[52:53], v[46:47] op_sel_hi:[0,1]
	v_add_f32_dpp v58, v58, v58 quad_perm:[1,0,3,2] row_mask:0xf bank_mask:0xf bound_ctrl:1
	v_pk_fma_f32 v[60:61], v[4:5], v[28:29], v[60:61]
	v_add_f32_e32 v67, v64, v65
	v_add_f32_dpp v58, v58, v58 quad_perm:[2,3,0,1] row_mask:0xf bank_mask:0xf bound_ctrl:1
	v_pk_fma_f32 v[62:63], v[6:7], v[30:31], v[62:63]
	v_add_f32_dpp v69, v66, v66 row_mirror row_mask:0xf bank_mask:0x3
	v_add_f32_dpp v58, v58, v58 row_half_mirror row_mask:0xf bank_mask:0xf bound_ctrl:1
	s_nop 0
	v_add_f32_dpp v69, v67, v67 row_mirror row_mask:0xf bank_mask:0xc
	ds_read_b128 v[20:23], v76 offset:35328
	v_add_f32_dpp v58, v58, v58 row_mirror row_mask:0xf bank_mask:0xf bound_ctrl:1
	v_pk_fma_f32 v[4:5], v[58:59], v[36:37], v[60:61] op_sel_hi:[0,1,1]
	v_pk_fma_f32 v[6:7], v[58:59], v[38:39], v[62:63] op_sel_hi:[0,1,1]
	s_waitcnt lgkmcnt(6)
	ds_read_b128 v[32:35], v76 offset:27392
	ds_read_b128 v[44:47], v76 offset:39680
	ds_read_b128 v[28:31], v76 offset:23296
	ds_read_b128 v[36:39], v76 offset:31488
	ds_read_b128 v[48:51], v77 offset:42016
	v_pk_mul_f32 v[56:57], v[4:5], v[228:229]
	v_pk_mul_f32 v[64:65], v[4:5], v[40:41]
	v_pk_fma_f32 v[56:57], v[6:7], v[230:231], v[56:57]
	v_pk_fma_f32 v[64:65], v[6:7], v[42:43], v[64:65]
	v_add_f32_e32 v58, v56, v57
	v_pk_mul_f32 v[60:61], v[52:53], v[240:241] op_sel:[1,0] op_sel_hi:[1,1]
	v_pk_mul_f32 v[62:63], v[52:53], v[242:243] op_sel:[1,0] op_sel_hi:[1,1]
	v_add_f32_dpp v58, v58, v58 quad_perm:[1,0,3,2] row_mask:0xf bank_mask:0xf bound_ctrl:1
	v_pk_fma_f32 v[60:61], v[4:5], v[224:225], v[60:61]
	v_add_f32_e32 v66, v64, v65
	v_add_f32_dpp v58, v58, v58 quad_perm:[2,3,0,1] row_mask:0xf bank_mask:0xf bound_ctrl:1
	v_pk_fma_f32 v[62:63], v[6:7], v[226:227], v[62:63]
	v_add_f32_dpp v68, v68, v68 row_half_mirror row_mask:0xf bank_mask:0x5
	v_add_f32_dpp v58, v58, v58 row_half_mirror row_mask:0xf bank_mask:0xf bound_ctrl:1
	s_nop 0
	v_add_f32_dpp v68, v69, v69 row_half_mirror row_mask:0xf bank_mask:0xa
	ds_read_b128 v[40:43], v76 offset:35584
	v_add_f32_dpp v58, v58, v58 row_mirror row_mask:0xf bank_mask:0xf bound_ctrl:1
	v_pk_fma_f32 v[4:5], v[58:59], v[232:233], v[60:61] op_sel_hi:[0,1,1]
	v_pk_fma_f32 v[6:7], v[58:59], v[234:235], v[62:63] op_sel_hi:[0,1,1]
	s_waitcnt lgkmcnt(7)
	ds_read_b128 v[228:231], v76 offset:27648
	ds_read_b128 v[240:243], v76 offset:39936
	ds_read_b128 v[224:227], v76 offset:23552
	ds_read_b128 v[232:235], v76 offset:31744
	v_pk_mul_f32 v[56:57], v[4:5], v[12:13]
	v_pk_mul_f32 v[64:65], v[4:5], v[236:237]
	v_pk_fma_f32 v[56:57], v[6:7], v[14:15], v[56:57]
	v_pk_fma_f32 v[64:65], v[6:7], v[238:239], v[64:65]
	v_add_f32_e32 v58, v56, v57
	v_pk_mul_f32 v[60:61], v[54:55], v[24:25] op_sel_hi:[0,1]
	v_pk_mul_f32 v[62:63], v[54:55], v[26:27] op_sel_hi:[0,1]
	v_add_f32_dpp v58, v58, v58 quad_perm:[1,0,3,2] row_mask:0xf bank_mask:0xf bound_ctrl:1
	v_pk_fma_f32 v[60:61], v[4:5], v[8:9], v[60:61]
	v_add_f32_e32 v67, v64, v65
	v_add_f32_dpp v58, v58, v58 quad_perm:[2,3,0,1] row_mask:0xf bank_mask:0xf bound_ctrl:1
	v_pk_fma_f32 v[62:63], v[6:7], v[10:11], v[62:63]
	v_add_f32_dpp v70, v66, v66 row_mirror row_mask:0xf bank_mask:0x3
	v_add_f32_dpp v58, v58, v58 row_half_mirror row_mask:0xf bank_mask:0xf bound_ctrl:1
	s_nop 0
	v_add_f32_dpp v70, v67, v67 row_mirror row_mask:0xf bank_mask:0xc
	ds_read_b128 v[236:239], v76 offset:35840
	v_add_f32_dpp v58, v58, v58 row_mirror row_mask:0xf bank_mask:0xf bound_ctrl:1
	v_pk_fma_f32 v[4:5], v[58:59], v[16:17], v[60:61] op_sel_hi:[0,1,1]
	v_pk_fma_f32 v[6:7], v[58:59], v[18:19], v[62:63] op_sel_hi:[0,1,1]
	s_waitcnt lgkmcnt(7)
; DI void scan_task(const Params& p, int l, int isP, int b, int h, int rg, char* smem, const bool dry) {
;     ...
;     for (int s = 0; s < 32; s++) {
;       f32x4 w4n = w4, a4n = a4, b4n = b4;
;       uint2 urn = ur, ukn = uk;
;       float vn = v;
;       if (s < 31) {
;         w4n = *(const f32x4*)(fw + (s + 1) * 64);
;         a4n = *(const f32x4*)(fa + (s + 1) * 64);
;         b4n = *(const f32x4*)(fb + (s + 1) * 64);
;         urn = *(const uint2*)(pr + (s + 1) * 128);
;         ukn = *(const uint2*)(pk + (s + 1) * 128);
;         vn = vb[(s + 1) * 16];
;       }
;       __builtin_amdgcn_sched_barrier(0);
;       const f32x2 klo = {__uint_as_float(uk.x << 16), __uint_as_float(uk.x & 0xFFFF0000u)};
;       const f32x2 khi = {__uint_as_float(uk.y << 16), __uint_as_float(uk.y & 0xFFFF0000u)};
;       const f32x2 rlo = {__uint_as_float(ur.x << 16), __uint_as_float(ur.x & 0xFFFF0000u)};
;       const f32x2 rhi = {__uint_as_float(ur.y << 16), __uint_as_float(ur.y & 0xFFFF0000u)};
;       const f32x2 vv = {v, v};
;       const f32x2 t = Sa * a4.lo + Sb * a4.hi;
;       const f32x2 na = Sa * w4.lo + vv * klo;
;       const f32x2 nb = Sb * w4.hi + vv * khi;
;       float sa = t.x + t.y;
;       float yp = yprev;
;       rowsum16x2(sa, yp);
;       if (s >= 1 && s <= 16) ykeep0 = (jq == s - 1) ? yp : ykeep0;
;       if (s >= 17) ykeep1 = (jq == s - 17) ? yp : ykeep1;
;       const f32x2 sv = {sa, sa};
;       Sa = na + sv * b4.lo;
;       Sb = nb + sv * b4.hi;
;       const f32x2 yy = Sa * rlo + Sb * rhi;
;       yprev = yy.x + yy.y;
;       w4 = w4n; a4 = a4n; b4 = b4n; ur = urn; uk = ukn; v = vn;
;     }
	ds_read_b128 v[12:15], v76 offset:27904
	ds_read_b128 v[24:27], v76 offset:40192
	ds_read_b128 v[8:11], v76 offset:23808
	ds_read_b128 v[16:19], v76 offset:32000
	v_pk_mul_f32 v[56:57], v[4:5], v[32:33]
	v_pk_mul_f32 v[64:65], v[4:5], v[20:21]
	v_pk_fma_f32 v[56:57], v[6:7], v[34:35], v[56:57]
	v_pk_fma_f32 v[64:65], v[6:7], v[22:23], v[64:65]
	v_add_f32_e32 v58, v56, v57
	v_pk_mul_f32 v[60:61], v[54:55], v[44:45] op_sel:[1,0] op_sel_hi:[1,1]
	v_pk_mul_f32 v[62:63], v[54:55], v[46:47] op_sel:[1,0] op_sel_hi:[1,1]
	v_add_f32_dpp v58, v58, v58 quad_perm:[1,0,3,2] row_mask:0xf bank_mask:0xf bound_ctrl:1
	v_pk_fma_f32 v[60:61], v[4:5], v[28:29], v[60:61]
	v_add_f32_e32 v66, v64, v65
	v_add_f32_dpp v58, v58, v58 quad_perm:[2,3,0,1] row_mask:0xf bank_mask:0xf bound_ctrl:1
	v_pk_fma_f32 v[62:63], v[6:7], v[30:31], v[62:63]
	s_nop 0
	v_add_f32_dpp v58, v58, v58 row_half_mirror row_mask:0xf bank_mask:0xf bound_ctrl:1
	ds_read_b128 v[20:23], v76 offset:36096
	s_nop 0
	v_add_f32_dpp v58, v58, v58 row_mirror row_mask:0xf bank_mask:0xf bound_ctrl:1
	v_pk_fma_f32 v[4:5], v[58:59], v[36:37], v[60:61] op_sel_hi:[0,1,1]
	v_pk_fma_f32 v[6:7], v[58:59], v[38:39], v[62:63] op_sel_hi:[0,1,1]
	s_waitcnt lgkmcnt(6)
	ds_read_b128 v[32:35], v76 offset:28160
	ds_read_b128 v[44:47], v76 offset:40448
	ds_read_b128 v[28:31], v76 offset:24064
	ds_read_b128 v[36:39], v76 offset:32256
	v_pk_mul_f32 v[56:57], v[4:5], v[228:229]
	v_pk_mul_f32 v[64:65], v[4:5], v[40:41]
	v_pk_fma_f32 v[56:57], v[6:7], v[230:231], v[56:57]
	v_pk_fma_f32 v[64:65], v[6:7], v[42:43], v[64:65]
	v_add_f32_e32 v58, v56, v57
	v_pk_mul_f32 v[60:61], v[48:49], v[240:241] op_sel_hi:[0,1]
	v_pk_mul_f32 v[62:63], v[48:49], v[242:243] op_sel_hi:[0,1]
	v_add_f32_dpp v58, v58, v58 quad_perm:[1,0,3,2] row_mask:0xf bank_mask:0xf bound_ctrl:1
	v_pk_fma_f32 v[60:61], v[4:5], v[224:225], v[60:61]
	v_add_f32_e32 v67, v64, v65
	v_add_f32_dpp v58, v58, v58 quad_perm:[2,3,0,1] row_mask:0xf bank_mask:0xf bound_ctrl:1
	v_pk_fma_f32 v[62:63], v[6:7], v[226:227], v[62:63]
	v_add_f32_dpp v71, v66, v66 row_mirror row_mask:0xf bank_mask:0x3
	v_add_f32_dpp v58, v58, v58 row_half_mirror row_mask:0xf bank_mask:0xf bound_ctrl:1
	s_nop 0
	v_add_f32_dpp v71, v67, v67 row_mirror row_mask:0xf bank_mask:0xc
	ds_read_b128 v[40:43], v76 offset:36352
	v_add_f32_dpp v58, v58, v58 row_mirror row_mask:0xf bank_mask:0xf bound_ctrl:1
	v_pk_fma_f32 v[4:5], v[58:59], v[232:233], v[60:61] op_sel_hi:[0,1,1]
	v_pk_fma_f32 v[6:7], v[58:59], v[234:235], v[62:63] op_sel_hi:[0,1,1]
	s_waitcnt lgkmcnt(6)
	ds_read_b128 v[228:231], v76 offset:28416
	ds_read_b128 v[240:243], v76 offset:40704
	ds_read_b128 v[224:227], v76 offset:24320
	ds_read_b128 v[232:235], v76 offset:32512
	ds_read_b128 v[52:55], v77 offset:42032
	v_pk_mul_f32 v[56:57], v[4:5], v[12:13]
	v_pk_mul_f32 v[64:65], v[4:5], v[236:237]
	v_pk_fma_f32 v[56:57], v[6:7], v[14:15], v[56:57]
	v_pk_fma_f32 v[64:65], v[6:7], v[238:239], v[64:65]
	v_add_f32_e32 v58, v56, v57
	v_pk_mul_f32 v[60:61], v[48:49], v[24:25] op_sel:[1,0] op_sel_hi:[1,1]
	v_pk_mul_f32 v[62:63], v[48:49], v[26:27] op_sel:[1,0] op_sel_hi:[1,1]
	v_add_f32_dpp v58, v58, v58 quad_perm:[1,0,3,2] row_mask:0xf bank_mask:0xf bound_ctrl:1
	v_pk_fma_f32 v[60:61], v[4:5], v[8:9], v[60:61]
	v_add_f32_e32 v66, v64, v65
	v_add_f32_dpp v58, v58, v58 quad_perm:[2,3,0,1] row_mask:0xf bank_mask:0xf bound_ctrl:1
	v_pk_fma_f32 v[62:63], v[6:7], v[10:11], v[62:63]
	v_add_f32_dpp v70, v70, v70 row_half_mirror row_mask:0xf bank_mask:0x5
	v_add_f32_dpp v58, v58, v58 row_half_mirror row_mask:0xf bank_mask:0xf bound_ctrl:1
	s_nop 0
	v_add_f32_dpp v70, v71, v71 row_half_mirror row_mask:0xf bank_mask:0xa
	ds_read_b128 v[236:239], v76 offset:36608
	v_add_f32_dpp v58, v58, v58 row_mirror row_mask:0xf bank_mask:0xf bound_ctrl:1
	v_pk_fma_f32 v[4:5], v[58:59], v[16:17], v[60:61] op_sel_hi:[0,1,1]
	v_pk_fma_f32 v[6:7], v[58:59], v[18:19], v[62:63] op_sel_hi:[0,1,1]
	s_waitcnt lgkmcnt(7)
	ds_read_b128 v[12:15], v76 offset:28672
	ds_read_b128 v[24:27], v76 offset:40960
	ds_read_b128 v[8:11], v76 offset:24576
	ds_read_b128 v[16:19], v76 offset:32768
	v_pk_mul_f32 v[56:57], v[4:5], v[32:33]
	v_pk_mul_f32 v[64:65], v[4:5], v[20:21]
	v_pk_fma_f32 v[56:57], v[6:7], v[34:35], v[56:57]
	v_pk_fma_f32 v[64:65], v[6:7], v[22:23], v[64:65]
	v_add_f32_e32 v58, v56, v57
	v_pk_mul_f32 v[60:61], v[50:51], v[44:45] op_sel_hi:[0,1]
	v_pk_mul_f32 v[62:63], v[50:51], v[46:47] op_sel_hi:[0,1]
	v_add_f32_dpp v58, v58, v58 quad_perm:[1,0,3,2] row_mask:0xf bank_mask:0xf bound_ctrl:1
	v_pk_fma_f32 v[60:61], v[4:5], v[28:29], v[60:61]
	v_add_f32_e32 v67, v64, v65
	v_add_f32_dpp v58, v58, v58 quad_perm:[2,3,0,1] row_mask:0xf bank_mask:0xf bound_ctrl:1
	v_pk_fma_f32 v[62:63], v[6:7], v[30:31], v[62:63]
	v_add_f32_dpp v72, v66, v66 row_mirror row_mask:0xf bank_mask:0x3
	v_add_f32_dpp v58, v58, v58 row_half_mirror row_mask:0xf bank_mask:0xf bound_ctrl:1
	s_nop 0
	v_add_f32_dpp v72, v67, v67 row_mirror row_mask:0xf bank_mask:0xc
	ds_read_b128 v[20:23], v76 offset:36864
	v_add_f32_dpp v58, v58, v58 row_mirror row_mask:0xf bank_mask:0xf bound_ctrl:1
	v_pk_fma_f32 v[4:5], v[58:59], v[36:37], v[60:61] op_sel_hi:[0,1,1]
	v_pk_fma_f32 v[6:7], v[58:59], v[38:39], v[62:63] op_sel_hi:[0,1,1]
	s_waitcnt lgkmcnt(7)
; DI void scan_task(const Params& p, int l, int isP, int b, int h, int rg, char* smem, const bool dry) {
;     ...
;     for (int s = 0; s < 32; s++) {
;       f32x4 w4n = w4, a4n = a4, b4n = b4;
;       uint2 urn = ur, ukn = uk;
;       float vn = v;
;       if (s < 31) {
;         w4n = *(const f32x4*)(fw + (s + 1) * 64);
;         a4n = *(const f32x4*)(fa + (s + 1) * 64);
;         b4n = *(const f32x4*)(fb + (s + 1) * 64);
;         urn = *(const uint2*)(pr + (s + 1) * 128);
;         ukn = *(const uint2*)(pk + (s + 1) * 128);
;         vn = vb[(s + 1) * 16];
;       }
;       __builtin_amdgcn_sched_barrier(0);
;       const f32x2 klo = {__uint_as_float(uk.x << 16), __uint_as_float(uk.x & 0xFFFF0000u)};
;       const f32x2 khi = {__uint_as_float(uk.y << 16), __uint_as_float(uk.y & 0xFFFF0000u)};
;       const f32x2 rlo = {__uint_as_float(ur.x << 16), __uint_as_float(ur.x & 0xFFFF0000u)};
;       const f32x2 rhi = {__uint_as_float(ur.y << 16), __uint_as_float(ur.y & 0xFFFF0000u)};
;       const f32x2 vv = {v, v};
;       const f32x2 t = Sa * a4.lo + Sb * a4.hi;
;       const f32x2 na = Sa * w4.lo + vv * klo;
;       const f32x2 nb = Sb * w4.hi + vv * khi;
;       float sa = t.x + t.y;
;       float yp = yprev;
;       rowsum16x2(sa, yp);
;       if (s >= 1 && s <= 16) ykeep0 = (jq == s - 1) ? yp : ykeep0;
;       if (s >= 17) ykeep1 = (jq == s - 17) ? yp : ykeep1;
;       const f32x2 sv = {sa, sa};
;       Sa = na + sv * b4.lo;
;       Sb = nb + sv * b4.hi;
;       const f32x2 yy = Sa * rlo + Sb * rhi;
;       yprev = yy.x + yy.y;
;       w4 = w4n; a4 = a4n; b4 = b4n; ur = urn; uk = ukn; v = vn;
;     }
;     {
;       const float yl = rowsum16(yprev);
;       ykeep1 = (jq == 15) ? yl : ykeep1;
;     }
;     if (!dry) { yo[0] = ykeep0; yo[(size_t)16 * 512] = ykeep1; }
;     if (more) sstore((c + 1) & 1);
;     __syncthreads();
	ds_read_b128 v[32:35], v76 offset:28928
	ds_read_b128 v[44:47], v76 offset:41216
	ds_read_b128 v[28:31], v76 offset:24832
	ds_read_b128 v[36:39], v76 offset:33024
	v_pk_mul_f32 v[56:57], v[4:5], v[228:229]
	v_pk_mul_f32 v[64:65], v[4:5], v[40:41]
	v_pk_fma_f32 v[56:57], v[6:7], v[230:231], v[56:57]
	v_pk_fma_f32 v[64:65], v[6:7], v[42:43], v[64:65]
	v_add_f32_e32 v58, v56, v57
	v_pk_mul_f32 v[60:61], v[50:51], v[240:241] op_sel:[1,0] op_sel_hi:[1,1]
	v_pk_mul_f32 v[62:63], v[50:51], v[242:243] op_sel:[1,0] op_sel_hi:[1,1]
	v_add_f32_dpp v58, v58, v58 quad_perm:[1,0,3,2] row_mask:0xf bank_mask:0xf bound_ctrl:1
	v_pk_fma_f32 v[60:61], v[4:5], v[224:225], v[60:61]
	v_add_f32_e32 v66, v64, v65
	v_add_f32_dpp v58, v58, v58 quad_perm:[2,3,0,1] row_mask:0xf bank_mask:0xf bound_ctrl:1
	v_pk_fma_f32 v[62:63], v[6:7], v[226:227], v[62:63]
	s_nop 0
	v_add_f32_dpp v58, v58, v58 row_half_mirror row_mask:0xf bank_mask:0xf bound_ctrl:1
	ds_read_b128 v[40:43], v76 offset:37120
	s_nop 0
	v_add_f32_dpp v58, v58, v58 row_mirror row_mask:0xf bank_mask:0xf bound_ctrl:1
	v_pk_fma_f32 v[4:5], v[58:59], v[232:233], v[60:61] op_sel_hi:[0,1,1]
	v_pk_fma_f32 v[6:7], v[58:59], v[234:235], v[62:63] op_sel_hi:[0,1,1]
	s_waitcnt lgkmcnt(6)
	ds_read_b128 v[228:231], v76 offset:29184
	ds_read_b128 v[240:243], v76 offset:41472
	ds_read_b128 v[224:227], v76 offset:25088
	ds_read_b128 v[232:235], v76 offset:33280
	v_pk_mul_f32 v[56:57], v[4:5], v[12:13]
	v_pk_mul_f32 v[64:65], v[4:5], v[236:237]
	v_pk_fma_f32 v[56:57], v[6:7], v[14:15], v[56:57]
	v_pk_fma_f32 v[64:65], v[6:7], v[238:239], v[64:65]
	v_add_f32_e32 v58, v56, v57
	v_pk_mul_f32 v[60:61], v[52:53], v[24:25] op_sel_hi:[0,1]
	v_pk_mul_f32 v[62:63], v[52:53], v[26:27] op_sel_hi:[0,1]
	v_add_f32_dpp v58, v58, v58 quad_perm:[1,0,3,2] row_mask:0xf bank_mask:0xf bound_ctrl:1
	v_pk_fma_f32 v[60:61], v[4:5], v[8:9], v[60:61]
	v_add_f32_e32 v67, v64, v65
	v_add_f32_dpp v58, v58, v58 quad_perm:[2,3,0,1] row_mask:0xf bank_mask:0xf bound_ctrl:1
	v_pk_fma_f32 v[62:63], v[6:7], v[10:11], v[62:63]
	v_add_f32_dpp v73, v66, v66 row_mirror row_mask:0xf bank_mask:0x3
	v_add_f32_dpp v58, v58, v58 row_half_mirror row_mask:0xf bank_mask:0xf bound_ctrl:1
	s_nop 0
	v_add_f32_dpp v73, v67, v67 row_mirror row_mask:0xf bank_mask:0xc
	ds_read_b128 v[236:239], v76 offset:37376
	v_add_f32_dpp v58, v58, v58 row_mirror row_mask:0xf bank_mask:0xf bound_ctrl:1
	v_pk_fma_f32 v[4:5], v[58:59], v[16:17], v[60:61] op_sel_hi:[0,1,1]
	v_pk_fma_f32 v[6:7], v[58:59], v[18:19], v[62:63] op_sel_hi:[0,1,1]
	s_waitcnt lgkmcnt(6)
	ds_read_b128 v[12:15], v76 offset:29440
	ds_read_b128 v[24:27], v76 offset:41728
	ds_read_b128 v[8:11], v76 offset:25344
	ds_read_b128 v[16:19], v76 offset:33536
	v_pk_mul_f32 v[56:57], v[4:5], v[32:33]
	v_pk_mul_f32 v[64:65], v[4:5], v[20:21]
	v_pk_fma_f32 v[56:57], v[6:7], v[34:35], v[56:57]
	v_pk_fma_f32 v[64:65], v[6:7], v[22:23], v[64:65]
	v_add_f32_e32 v58, v56, v57
	v_pk_mul_f32 v[60:61], v[52:53], v[44:45] op_sel:[1,0] op_sel_hi:[1,1]
	v_pk_mul_f32 v[62:63], v[52:53], v[46:47] op_sel:[1,0] op_sel_hi:[1,1]
	v_add_f32_dpp v58, v58, v58 quad_perm:[1,0,3,2] row_mask:0xf bank_mask:0xf bound_ctrl:1
	v_pk_fma_f32 v[60:61], v[4:5], v[28:29], v[60:61]
	v_add_f32_e32 v66, v64, v65
	v_add_f32_dpp v58, v58, v58 quad_perm:[2,3,0,1] row_mask:0xf bank_mask:0xf bound_ctrl:1
	v_pk_fma_f32 v[62:63], v[6:7], v[30:31], v[62:63]
	v_add_f32_dpp v72, v72, v72 row_half_mirror row_mask:0xf bank_mask:0x5
	v_add_f32_dpp v58, v58, v58 row_half_mirror row_mask:0xf bank_mask:0xf bound_ctrl:1
	s_nop 0
	v_add_f32_dpp v72, v73, v73 row_half_mirror row_mask:0xf bank_mask:0xa
	ds_read_b128 v[20:23], v76 offset:37632
	v_add_f32_dpp v58, v58, v58 row_mirror row_mask:0xf bank_mask:0xf bound_ctrl:1
	v_pk_fma_f32 v[4:5], v[58:59], v[36:37], v[60:61] op_sel_hi:[0,1,1]
	v_pk_fma_f32 v[6:7], v[58:59], v[38:39], v[62:63] op_sel_hi:[0,1,1]
	s_waitcnt lgkmcnt(6)
	v_pk_mul_f32 v[56:57], v[4:5], v[228:229]
	v_pk_mul_f32 v[64:65], v[4:5], v[40:41]
	v_pk_fma_f32 v[56:57], v[6:7], v[230:231], v[56:57]
	v_pk_fma_f32 v[64:65], v[6:7], v[42:43], v[64:65]
	v_add_f32_e32 v58, v56, v57
	v_pk_mul_f32 v[60:61], v[54:55], v[240:241] op_sel_hi:[0,1]
	v_pk_mul_f32 v[62:63], v[54:55], v[242:243] op_sel_hi:[0,1]
	v_add_f32_dpp v58, v58, v58 quad_perm:[1,0,3,2] row_mask:0xf bank_mask:0xf bound_ctrl:1
	v_pk_fma_f32 v[60:61], v[4:5], v[224:225], v[60:61]
	v_add_f32_e32 v67, v64, v65
	v_add_f32_dpp v58, v58, v58 quad_perm:[2,3,0,1] row_mask:0xf bank_mask:0xf bound_ctrl:1
	v_pk_fma_f32 v[62:63], v[6:7], v[226:227], v[62:63]
	v_add_f32_dpp v74, v66, v66 row_mirror row_mask:0xf bank_mask:0x3
	v_add_f32_dpp v58, v58, v58 row_half_mirror row_mask:0xf bank_mask:0xf bound_ctrl:1
	s_nop 0
	v_add_f32_dpp v74, v67, v67 row_mirror row_mask:0xf bank_mask:0xc
	v_add_f32_dpp v58, v58, v58 row_mirror row_mask:0xf bank_mask:0xf bound_ctrl:1
	v_pk_fma_f32 v[4:5], v[58:59], v[232:233], v[60:61] op_sel_hi:[0,1,1]
	v_pk_fma_f32 v[6:7], v[58:59], v[234:235], v[62:63] op_sel_hi:[0,1,1]
	s_waitcnt lgkmcnt(1)
	v_pk_mul_f32 v[56:57], v[4:5], v[12:13]
	v_pk_mul_f32 v[64:65], v[4:5], v[236:237]
	v_pk_fma_f32 v[56:57], v[6:7], v[14:15], v[56:57]
	v_pk_fma_f32 v[64:65], v[6:7], v[238:239], v[64:65]
	v_add_f32_e32 v58, v56, v57
	v_pk_mul_f32 v[60:61], v[54:55], v[24:25] op_sel:[1,0] op_sel_hi:[1,1]
	v_pk_mul_f32 v[62:63], v[54:55], v[26:27] op_sel:[1,0] op_sel_hi:[1,1]
	v_add_f32_dpp v58, v58, v58 quad_perm:[1,0,3,2] row_mask:0xf bank_mask:0xf bound_ctrl:1
	v_pk_fma_f32 v[60:61], v[4:5], v[8:9], v[60:61]
	v_add_f32_e32 v66, v64, v65
	v_add_f32_dpp v58, v58, v58 quad_perm:[2,3,0,1] row_mask:0xf bank_mask:0xf bound_ctrl:1
	v_pk_fma_f32 v[62:63], v[6:7], v[10:11], v[62:63]
	s_nop 0
	v_add_f32_dpp v58, v58, v58 row_half_mirror row_mask:0xf bank_mask:0xf bound_ctrl:1
	s_nop 1
	v_add_f32_dpp v58, v58, v58 row_mirror row_mask:0xf bank_mask:0xf bound_ctrl:1
	v_pk_fma_f32 v[4:5], v[58:59], v[16:17], v[60:61] op_sel_hi:[0,1,1]
	v_pk_fma_f32 v[6:7], v[58:59], v[18:19], v[62:63] op_sel_hi:[0,1,1]
	s_waitcnt lgkmcnt(0)
	v_pk_mul_f32 v[64:65], v[4:5], v[20:21]
	v_pk_fma_f32 v[64:65], v[6:7], v[22:23], v[64:65]
	v_add_f32_e32 v67, v64, v65
	s_add_i32 s23, s16, 2
	s_cmp_lt_u32 s23, s17
	s_cbranch_scc0 .Lscan_lastB
	s_cmp_lg_u32 s22, 0
	s_cbranch_scc1 .Lscan_w6B
	s_waitcnt vmcnt(0)
	s_branch .Lscan_wdB

; DI void scan_task(const Params& p, int l, int isP, int b, int h, int rg, char* smem, const bool dry) {
;     ...
;     f32x4 w4 = *(const f32x4*)fw, a4 = *(const f32x4*)fa, b4 = *(const f32x4*)fb;
;     uint2 ur = *(const uint2*)pr, uk = *(const uint2*)pk;
;     float v = vb[0];
.LstgbB:
	ds_read_b128 v[12:15], v76 offset:4096
	ds_read_b128 v[24:27], v76 offset:16384
	ds_read_b128 v[48:51], v77 offset:20480
	ds_read_b128 v[8:11], v76 offset:0
	ds_read_b128 v[16:19], v76 offset:8192
	ds_read_b128 v[20:23], v76 offset:12288
	s_branch .Lscan_tailB
